# diff unit epilogue: last gain quad loaded with the other seven, no mid-epilogue full wait (stacked on v141)
# baseline (speedup 1.0000x reference)
.LBB0_561:
	v_mbcnt_lo_u32_b32 v64, -1, 0
	v_mbcnt_hi_u32_b32 v64, -1, v64
	v_mbcnt_lo_u32_b32 v65, -1, 0
	v_mbcnt_hi_u32_b32 v65, -1, v65
	s_lshl_b32 s20, s8, 1
	v_lshlrev_b32_e32 v64, 2, v64
	v_xor_b32_e32 v64, 0x80, v64
	ds_bpermute_b32 v64, v64, v128
	v_lshlrev_b32_e32 v65, 2, v65
	v_xor_b32_e32 v65, 0x80, v65
	ds_bpermute_b32 v65, v65, v129
	s_mov_b32 s9, s21
	s_waitcnt lgkmcnt(0)
	v_add_f32_e32 v64, v128, v64
	v_div_scale_f32 v66, s[10:11], v64, v64, 1.0
	v_rcp_f32_e32 v67, v66
	v_add_f32_e32 v65, v129, v65
	v_writelane_b32 v252, s8, 43
	v_lshlrev_b32_e32 v160, 1, v182
	v_fma_f32 v68, -v66, v67, 1.0
	v_fmac_f32_e32 v67, v68, v67
	v_div_scale_f32 v68, vcc, 1.0, v64, 1.0
	v_mul_f32_e32 v69, v68, v67
	v_fma_f32 v70, -v66, v69, v68
	v_fmac_f32_e32 v69, v70, v67
	v_fma_f32 v66, -v66, v69, v68
	v_div_fmas_f32 v66, v66, v67, v69
	v_div_fixup_f32 v64, v66, v64, 1.0
	v_div_scale_f32 v66, s[10:11], v65, v65, v120
	v_rcp_f32_e32 v67, v66
	v_readlane_b32 s10, v255, 5
	v_readlane_b32 s11, v255, 6
	v_writelane_b32 v252, s9, 44
	v_fma_f32 v68, -v66, v67, 1.0
	v_fmac_f32_e32 v67, v68, v67
	v_div_scale_f32 v68, vcc, v120, v65, v120
	v_mul_f32_e32 v69, v68, v67
	v_fma_f32 v70, -v66, v69, v68
	v_fmac_f32_e32 v69, v70, v67
	v_fma_f32 v66, -v66, v69, v68
	v_div_fmas_f32 v66, v66, v67, v69
	v_div_fixup_f32 v66, v66, v65, v120
	v_pk_mul_f32 v[26:27], v[26:27], v[66:67] op_sel_hi:[1,0]
	s_mov_b64 s[8:9], s[0:1]
	v_pk_fma_f32 v[68:69], v[10:11], v[64:65], v[26:27] op_sel_hi:[1,0,1] neg_lo:[0,0,1] neg_hi:[0,0,1]
	v_pk_mul_f32 v[10:11], v[28:29], v[66:67] op_sel_hi:[1,0]
	v_pk_mul_f32 v[62:63], v[62:63], v[66:67] op_sel_hi:[1,0]
	v_pk_fma_f32 v[10:11], v[12:13], v[64:65], v[10:11] op_sel_hi:[1,0,1] neg_lo:[0,0,1] neg_hi:[0,0,1]
	v_pk_mul_f32 v[12:13], v[30:31], v[66:67] op_sel_hi:[1,0]
	v_pk_mul_f32 v[18:19], v[18:19], v[66:67] op_sel_hi:[1,0]
	v_pk_fma_f32 v[12:13], v[14:15], v[64:65], v[12:13] op_sel_hi:[1,0,1] neg_lo:[0,0,1] neg_hi:[0,0,1]
	v_mbcnt_lo_u32_b32 v14, -1, 0
	v_mbcnt_hi_u32_b32 v14, -1, v14
	v_pk_mul_f32 v[50:51], v[50:51], v[66:67] op_sel_hi:[1,0]
	v_lshlrev_b32_e32 v14, 2, v14
	v_xor_b32_e32 v65, 0x80, v14
	v_lshlrev_b64 v[14:15], 11, v[122:123]
	v_lshl_add_u64 v[14:15], s[10:11], 0, v[14:15]
	v_lshl_add_u64 v[14:15], v[14:15], 0, s[20:21]
	v_lshl_add_u64 v[14:15], v[14:15], 0, v[160:161]
	v_lshlrev_b32_e32 v160, 2, v182
	v_lshl_add_u64 v[26:27], s[8:9], 0, v[160:161]
	v_pk_fma_f32 v[62:63], v[46:47], v[64:65], v[62:63] op_sel_hi:[1,0,1] neg_lo:[0,0,1] neg_hi:[0,0,1]
	v_pk_mul_f32 v[46:47], v[60:61], v[66:67] op_sel_hi:[1,0]
	v_pk_fma_f32 v[92:93], v[2:3], v[64:65], v[18:19] op_sel_hi:[1,0,1] neg_lo:[0,0,1] neg_hi:[0,0,1]
	v_pk_mul_f32 v[2:3], v[16:17], v[66:67] op_sel_hi:[1,0]
	v_pk_fma_f32 v[60:61], v[44:45], v[64:65], v[46:47] op_sel_hi:[1,0,1] neg_lo:[0,0,1] neg_hi:[0,0,1]
	flat_load_dwordx4 v[44:47], v[26:27] offset:128
	v_pk_fma_f32 v[96:97], v[0:1], v[64:65], v[2:3] op_sel_hi:[1,0,1] neg_lo:[0,0,1] neg_hi:[0,0,1]
	flat_load_dwordx4 v[0:3], v[26:27] offset:160
	v_pk_mul_f32 v[16:17], v[22:23], v[66:67] op_sel_hi:[1,0]
	v_pk_fma_f32 v[50:51], v[34:35], v[64:65], v[50:51] op_sel_hi:[1,0,1] neg_lo:[0,0,1] neg_hi:[0,0,1]
	v_pk_fma_f32 v[6:7], v[6:7], v[64:65], v[16:17] op_sel_hi:[1,0,1] neg_lo:[0,0,1] neg_hi:[0,0,1]
	v_pk_mul_f32 v[16:17], v[20:21], v[66:67] op_sel_hi:[1,0]
	v_pk_mul_f32 v[34:35], v[48:49], v[66:67] op_sel_hi:[1,0]
	v_pk_fma_f32 v[20:21], v[4:5], v[64:65], v[16:17] op_sel_hi:[1,0,1] neg_lo:[0,0,1] neg_hi:[0,0,1]
	flat_load_dwordx4 v[16:19], v[26:27] offset:192
	v_pk_fma_f32 v[48:49], v[32:33], v[64:65], v[34:35] op_sel_hi:[1,0,1] neg_lo:[0,0,1] neg_hi:[0,0,1]
	v_pk_mul_f32 v[54:55], v[54:55], v[66:67] op_sel_hi:[1,0]
	v_pk_mul_f32 v[58:59], v[58:59], v[66:67] op_sel_hi:[1,0]
	v_pk_mul_f32 v[78:79], v[48:49], v[48:49]
	v_pk_fma_f32 v[54:55], v[38:39], v[64:65], v[54:55] op_sel_hi:[1,0,1] neg_lo:[0,0,1] neg_hi:[0,0,1]
	v_pk_mul_f32 v[38:39], v[52:53], v[66:67] op_sel_hi:[1,0]
	v_pk_fma_f32 v[58:59], v[42:43], v[64:65], v[58:59] op_sel_hi:[1,0,1] neg_lo:[0,0,1] neg_hi:[0,0,1]
	v_pk_mul_f32 v[42:43], v[56:57], v[66:67] op_sel_hi:[1,0]
	v_pk_mul_f32 v[24:25], v[24:25], v[66:67] op_sel_hi:[1,0]
	v_pk_mul_f32 v[76:77], v[50:51], v[50:51]
	v_pk_fma_f32 v[52:53], v[36:37], v[64:65], v[38:39] op_sel_hi:[1,0,1] neg_lo:[0,0,1] neg_hi:[0,0,1]
	v_pk_fma_f32 v[56:57], v[40:41], v[64:65], v[42:43] op_sel_hi:[1,0,1] neg_lo:[0,0,1] neg_hi:[0,0,1]
	v_pk_fma_f32 v[8:9], v[8:9], v[64:65], v[24:25] op_sel_hi:[1,0,1] neg_lo:[0,0,1] neg_hi:[0,0,1]
	v_add_f32_e32 v64, v78, v79
	v_add_f32_e32 v64, v76, v64
	v_pk_mul_f32 v[82:83], v[52:53], v[52:53]
	v_add_f32_e32 v64, v77, v64
	v_add_f32_e32 v64, v82, v64
	v_pk_mul_f32 v[80:81], v[54:55], v[54:55]
	v_add_f32_e32 v64, v83, v64
	v_add_f32_e32 v64, v80, v64
	v_pk_mul_f32 v[86:87], v[56:57], v[56:57]
	v_add_f32_e32 v64, v81, v64
	v_add_f32_e32 v64, v86, v64
	v_pk_mul_f32 v[84:85], v[58:59], v[58:59]
	v_add_f32_e32 v64, v87, v64
	v_add_f32_e32 v64, v84, v64
	v_pk_mul_f32 v[90:91], v[60:61], v[60:61]
	v_add_f32_e32 v64, v85, v64
	v_add_f32_e32 v64, v90, v64
	v_pk_mul_f32 v[88:89], v[62:63], v[62:63]
	v_add_f32_e32 v64, v91, v64
	v_add_f32_e32 v64, v88, v64
	v_pk_mul_f32 v[98:99], v[96:97], v[96:97]
	v_add_f32_e32 v64, v89, v64
	v_add_f32_e32 v64, v98, v64
	v_pk_mul_f32 v[94:95], v[92:93], v[92:93]
	v_add_f32_e32 v64, v99, v64
	v_add_f32_e32 v64, v94, v64
	v_pk_mul_f32 v[4:5], v[20:21], v[20:21]
	v_add_f32_e32 v64, v95, v64
	v_add_f32_e32 v4, v4, v64
	v_pk_mul_f32 v[22:23], v[6:7], v[6:7]
	v_add_f32_e32 v4, v5, v4
	v_add_f32_e32 v4, v22, v4
	v_pk_mul_f32 v[24:25], v[8:9], v[8:9]
	v_add_f32_e32 v4, v23, v4
	v_add_f32_e32 v4, v24, v4
	v_pk_mul_f32 v[70:71], v[68:69], v[68:69]
	v_add_f32_e32 v4, v25, v4
	v_add_f32_e32 v4, v70, v4
	v_pk_mul_f32 v[72:73], v[10:11], v[10:11]
	v_add_f32_e32 v4, v71, v4
	v_add_f32_e32 v4, v72, v4
	v_pk_mul_f32 v[74:75], v[12:13], v[12:13]
	v_add_f32_e32 v4, v73, v4
	v_add_f32_e32 v4, v74, v4
	v_add_f32_e32 v4, v75, v4
	ds_bpermute_b32 v5, v65, v4
	flat_load_dwordx4 v[28:31], v[26:27]
	flat_load_dwordx4 v[32:35], v[26:27] offset:32
	flat_load_dwordx4 v[36:39], v[26:27] offset:64
	flat_load_dwordx4 v[40:43], v[26:27] offset:96
	flat_load_dwordx4 v[232:235], v[26:27] offset:224
	s_waitcnt lgkmcnt(0)
	v_add_f32_e32 v4, v4, v5
	v_fmamk_f32 v4, v4, 0x3c800000, v208
	v_rsq_f32_e32 v4, v4
	s_add_i32 s14, s14, 0x98
	v_readlane_b32 s8, v255, 9
	s_cmp_ge_i32 s14, s8
	v_mul_f32_e32 v4, v121, v4
	v_pk_mul_f32 v[20:21], v[20:21], v[4:5] op_sel_hi:[1,0]
	v_pk_mul_f32 v[6:7], v[6:7], v[4:5] op_sel_hi:[1,0]
	s_waitcnt vmcnt(0)
	v_pk_mul_f32 v[0:1], v[0:1], v[20:21]
	v_pk_mul_f32 v[2:3], v[2:3], v[6:7]
	v_cvt_pk_bf16_f32 v0, v0, v1
	v_cvt_pk_bf16_f32 v1, v2, v3
	global_store_dwordx2 v[14:15], v[0:1], off offset:1104
	v_pk_mul_f32 v[0:1], v[8:9], v[4:5] op_sel_hi:[1,0]
	v_pk_mul_f32 v[2:3], v[68:69], v[4:5] op_sel_hi:[1,0]
	v_pk_mul_f32 v[0:1], v[16:17], v[0:1]
	v_pk_mul_f32 v[2:3], v[18:19], v[2:3]
	v_cvt_pk_bf16_f32 v0, v0, v1
	v_cvt_pk_bf16_f32 v1, v2, v3
	global_store_dwordx2 v[14:15], v[0:1], off offset:1120
	v_pk_mul_f32 v[22:23], v[48:49], v[4:5] op_sel_hi:[1,0]
	v_pk_mul_f32 v[24:25], v[50:51], v[4:5] op_sel_hi:[1,0]
	v_pk_mul_f32 v[6:7], v[10:11], v[4:5] op_sel_hi:[1,0]
	v_pk_mul_f32 v[22:23], v[28:29], v[22:23]
	v_pk_mul_f32 v[24:25], v[30:31], v[24:25]
	v_cvt_pk_bf16_f32 v22, v22, v23
	v_cvt_pk_bf16_f32 v23, v24, v25
	global_store_dwordx2 v[14:15], v[22:23], off offset:1024
	v_pk_mul_f32 v[22:23], v[52:53], v[4:5] op_sel_hi:[1,0]
	v_pk_mul_f32 v[24:25], v[54:55], v[4:5] op_sel_hi:[1,0]
	v_pk_mul_f32 v[22:23], v[32:33], v[22:23]
	v_pk_mul_f32 v[24:25], v[34:35], v[24:25]
	v_cvt_pk_bf16_f32 v22, v22, v23
	v_cvt_pk_bf16_f32 v23, v24, v25
	global_store_dwordx2 v[14:15], v[22:23], off offset:1040
	v_pk_mul_f32 v[22:23], v[56:57], v[4:5] op_sel_hi:[1,0]
	v_pk_mul_f32 v[24:25], v[58:59], v[4:5] op_sel_hi:[1,0]
	v_pk_mul_f32 v[22:23], v[36:37], v[22:23]
	v_pk_mul_f32 v[24:25], v[38:39], v[24:25]
	v_cvt_pk_bf16_f32 v22, v22, v23
	v_cvt_pk_bf16_f32 v23, v24, v25
	global_store_dwordx2 v[14:15], v[22:23], off offset:1056
	v_pk_mul_f32 v[22:23], v[60:61], v[4:5] op_sel_hi:[1,0]
	v_pk_mul_f32 v[24:25], v[62:63], v[4:5] op_sel_hi:[1,0]
	v_pk_mul_f32 v[22:23], v[40:41], v[22:23]
	v_pk_mul_f32 v[24:25], v[42:43], v[24:25]
	v_cvt_pk_bf16_f32 v22, v22, v23
	v_cvt_pk_bf16_f32 v23, v24, v25
	global_store_dwordx2 v[14:15], v[22:23], off offset:1072
	v_pk_mul_f32 v[22:23], v[96:97], v[4:5] op_sel_hi:[1,0]
	v_pk_mul_f32 v[24:25], v[92:93], v[4:5] op_sel_hi:[1,0]
	v_pk_mul_f32 v[4:5], v[12:13], v[4:5] op_sel_hi:[1,0]
	v_pk_mul_f32 v[22:23], v[44:45], v[22:23]
	v_pk_mul_f32 v[24:25], v[46:47], v[24:25]
	v_pk_mul_f32 v[0:1], v[232:233], v[6:7]
	v_pk_mul_f32 v[2:3], v[234:235], v[4:5]
	v_cvt_pk_bf16_f32 v22, v22, v23
	v_cvt_pk_bf16_f32 v23, v24, v25
	v_cvt_pk_bf16_f32 v0, v0, v1
	v_cvt_pk_bf16_f32 v1, v2, v3
	global_store_dwordx2 v[14:15], v[22:23], off offset:1088
	global_store_dwordx2 v[14:15], v[0:1], off offset:1136
	s_cbranch_scc1 .LBB0_584
	s_cmpk_lt_i32 s14, 0x100
	s_cbranch_scc1 .LBB0_584
